# gemm_in K loop: LDS-DMA destinations (M0) formed with scalar adds instead of a VALU + v_readfirstlane chain; loop header at 48 bytes past a 256-byte boundary
# speedup vs baseline: 1.0134x; 1.0134x over previous
.LBB0_299:
	s_lshl_b32 s40, s12, 7
	s_ashr_i32 s41, s40, 31
	s_lshl_b32 s0, s56, 7
	s_lshl_b64 s[42:43], s[40:41], 11
	s_add_u32 s44, s24, s42
	s_addc_u32 s45, s25, s43
	s_ashr_i32 s1, s0, 31
	s_lshl_b64 s[48:49], s[0:1], 11
	s_add_u32 s50, s5, s48
	v_readfirstlane_b32 s1, v67
	v_add_u32_e32 v4, 0x4000, v67
	s_waitcnt lgkmcnt(0)
	s_barrier
	s_addc_u32 s51, s96, s49
	v_lshl_add_u64 v[2:3], s[44:45], 0, v[92:93]
	s_mov_b32 m0, s1
	v_readfirstlane_b32 s1, v4
	v_add_u32_e32 v4, 0x1000, v67
	global_load_lds_dwordx4 v[2:3], off
	v_lshl_add_u64 v[2:3], s[50:51], 0, v[92:93]
	s_mov_b32 m0, s1
	v_readfirstlane_b32 s1, v4
	v_add_u32_e32 v4, 0x5000, v67
	global_load_lds_dwordx4 v[2:3], off
	v_lshl_add_u64 v[2:3], s[44:45], 0, v[94:95]
	s_mov_b32 m0, s1
	v_readfirstlane_b32 s1, v4
	v_add_u32_e32 v4, 0x2000, v67
	global_load_lds_dwordx4 v[2:3], off
	v_lshl_add_u64 v[2:3], s[50:51], 0, v[94:95]
	s_mov_b32 m0, s1
	v_readfirstlane_b32 s1, v4
	v_add_u32_e32 v4, 0x6000, v67
	global_load_lds_dwordx4 v[2:3], off
	v_lshl_add_u64 v[2:3], s[44:45], 0, v[96:97]
	s_mov_b32 m0, s1
	v_readfirstlane_b32 s1, v4
	v_add_u32_e32 v4, 0x3000, v67
	global_load_lds_dwordx4 v[2:3], off
	v_lshl_add_u64 v[2:3], s[50:51], 0, v[96:97]
	s_mov_b32 m0, s1
	v_readfirstlane_b32 s1, v4
	v_add_u32_e32 v4, 0x7000, v67
	global_load_lds_dwordx4 v[2:3], off
	v_lshl_add_u64 v[2:3], s[44:45], 0, v[98:99]
	s_mov_b32 m0, s1
	v_readfirstlane_b32 s1, v4
	global_load_lds_dwordx4 v[2:3], off
	v_lshl_add_u64 v[2:3], s[50:51], 0, v[98:99]
	s_mov_b32 m0, s1
	v_lshl_add_u64 v[100:101], v[76:77], 0, s[42:43]
	global_load_lds_dwordx4 v[2:3], off
	v_mov_b32_e32 v2, 0
	v_lshl_add_u64 v[102:103], v[78:79], 0, s[42:43]
	v_lshl_add_u64 v[104:105], v[80:81], 0, s[42:43]
	v_lshl_add_u64 v[106:107], v[82:83], 0, s[42:43]
	v_lshl_add_u64 v[108:109], v[84:85], 0, s[48:49]
	v_lshl_add_u64 v[110:111], v[86:87], 0, s[48:49]
	v_lshl_add_u64 v[112:113], v[88:89], 0, s[48:49]
	v_lshl_add_u64 v[114:115], v[90:91], 0, s[48:49]
	s_mov_b32 s13, 0
	s_mov_b64 s[42:43], 0
	v_mov_b32_e32 v3, v2
	v_mov_b32_e32 v4, v2
	v_mov_b32_e32 v5, v2
	v_mov_b32_e32 v6, v2
	v_mov_b32_e32 v7, v2
	v_mov_b32_e32 v8, v2
	v_mov_b32_e32 v9, v2
	v_mov_b32_e32 v10, v2
	v_mov_b32_e32 v11, v2
	v_mov_b32_e32 v12, v2
	v_mov_b32_e32 v13, v2
	v_mov_b32_e32 v14, v2
	v_mov_b32_e32 v15, v2
	v_mov_b32_e32 v16, v2
	v_mov_b32_e32 v17, v2
	v_mov_b32_e32 v18, v2
	v_mov_b32_e32 v19, v2
	v_mov_b32_e32 v20, v2
	v_mov_b32_e32 v21, v2
	v_mov_b32_e32 v22, v2
	v_mov_b32_e32 v23, v2
	v_mov_b32_e32 v24, v2
	v_mov_b32_e32 v25, v2
	v_mov_b32_e32 v26, v2
	v_mov_b32_e32 v27, v2
	v_mov_b32_e32 v28, v2
	v_mov_b32_e32 v29, v2
	v_mov_b32_e32 v30, v2
	v_mov_b32_e32 v31, v2
	v_mov_b32_e32 v32, v2
	v_mov_b32_e32 v33, v2
	v_mov_b32_e32 v34, v2
	v_mov_b32_e32 v35, v2
	v_mov_b32_e32 v36, v2
	v_mov_b32_e32 v37, v2
	v_mov_b32_e32 v38, v2
	v_mov_b32_e32 v39, v2
	v_mov_b32_e32 v40, v2
	v_mov_b32_e32 v41, v2
	v_mov_b32_e32 v42, v2
	v_mov_b32_e32 v43, v2
	v_mov_b32_e32 v44, v2
	v_mov_b32_e32 v45, v2
	v_mov_b32_e32 v46, v2
	v_mov_b32_e32 v47, v2
	v_mov_b32_e32 v48, v2
	v_mov_b32_e32 v49, v2
	v_mov_b32_e32 v50, v2
	v_mov_b32_e32 v51, v2
	v_mov_b32_e32 v52, v2
	v_mov_b32_e32 v53, v2
	v_mov_b32_e32 v54, v2
	v_mov_b32_e32 v55, v2
	v_mov_b32_e32 v56, v2
	v_mov_b32_e32 v57, v2
	v_mov_b32_e32 v58, v2
	v_mov_b32_e32 v59, v2
	v_mov_b32_e32 v60, v2
	v_mov_b32_e32 v61, v2
	v_mov_b32_e32 v62, v2
	v_mov_b32_e32 v63, v2
	v_mov_b32_e32 v64, v2
	v_mov_b32_e32 v65, v2
	.p2align 8
	s_nop 0
	s_nop 0
	s_nop 0
	s_nop 0
	s_nop 0
	s_nop 0
	s_nop 0
	s_nop 0
	s_nop 0
	s_nop 0
	s_nop 0
	s_nop 0
.LBB0_300:
	s_add_i32 s1, s13, 0x8000
	s_and_b32 s41, s1, 0x8000
	v_add_u32_e32 v122, s41, v67
	s_waitcnt vmcnt(0)
	v_add_u32_e32 v123, 0x4000, v122
	v_readfirstlane_b32 s41, v122
	s_waitcnt lgkmcnt(0)
	s_barrier
	s_mov_b32 m0, s41
	v_lshl_add_u64 v[120:121], v[100:101], 0, s[42:43]
	global_load_lds_dwordx4 v[120:121], off
	s_add_u32 m0, s41, 0x4000
	v_lshl_add_u64 v[120:121], v[108:109], 0, s[42:43]
	global_load_lds_dwordx4 v[120:121], off
	s_add_u32 m0, s41, 0x1000
	v_lshl_add_u64 v[120:121], v[102:103], 0, s[42:43]
	global_load_lds_dwordx4 v[120:121], off
	s_add_u32 m0, s41, 0x5000
	v_lshl_add_u64 v[120:121], v[110:111], 0, s[42:43]
	global_load_lds_dwordx4 v[120:121], off
	s_add_u32 m0, s41, 0x2000
	v_lshl_add_u64 v[120:121], v[104:105], 0, s[42:43]
	global_load_lds_dwordx4 v[120:121], off
	s_add_u32 m0, s41, 0x6000
	v_lshl_add_u64 v[120:121], v[112:113], 0, s[42:43]
	global_load_lds_dwordx4 v[120:121], off
	s_add_u32 m0, s41, 0x3000
	v_lshl_add_u64 v[120:121], v[106:107], 0, s[42:43]
	global_load_lds_dwordx4 v[120:121], off
	s_add_u32 m0, s41, 0x7000
	v_lshl_add_u64 v[120:121], v[114:115], 0, s[42:43]
	global_load_lds_dwordx4 v[120:121], off
	s_and_b32 s13, s13, 0x8000
	v_add_u32_e32 v124, s13, v116
	v_add_u32_e32 v151, v124, v117
	v_add_u32_e32 v160, v124, v118
	ds_read_b128 v[120:123], v151
	ds_read_b128 v[124:127], v160 offset:16384
	ds_read_b128 v[128:131], v151 offset:2048
	ds_read_b128 v[132:135], v160 offset:18432
	ds_read_b128 v[136:139], v151 offset:4096
	ds_read_b128 v[140:143], v160 offset:20480
	ds_read_b128 v[152:155], v151 offset:6144
	ds_read_b128 v[156:159], v160 offset:22528
	s_waitcnt lgkmcnt(0)
	v_mfma_f32_16x16x32_bf16 v[62:65], v[124:127], v[120:123], v[62:65]
	s_add_u32 s42, s42, 0x80
	s_addc_u32 s43, s43, 0
	s_cmpk_eq_i32 s42, 0x780
	v_mfma_f32_16x16x32_bf16 v[58:61], v[132:135], v[120:123], v[58:61]
	s_mov_b32 s13, s1
	v_mfma_f32_16x16x32_bf16 v[54:57], v[140:143], v[120:123], v[54:57]
	v_mfma_f32_16x16x32_bf16 v[50:53], v[156:159], v[120:123], v[50:53]
	v_mfma_f32_16x16x32_bf16 v[46:49], v[124:127], v[128:131], v[46:49]
	v_mfma_f32_16x16x32_bf16 v[42:45], v[132:135], v[128:131], v[42:45]
	v_mfma_f32_16x16x32_bf16 v[38:41], v[140:143], v[128:131], v[38:41]
	v_mfma_f32_16x16x32_bf16 v[34:37], v[156:159], v[128:131], v[34:37]
	v_mfma_f32_16x16x32_bf16 v[30:33], v[124:127], v[136:139], v[30:33]
	v_mfma_f32_16x16x32_bf16 v[26:29], v[132:135], v[136:139], v[26:29]
	v_mfma_f32_16x16x32_bf16 v[22:25], v[140:143], v[136:139], v[22:25]
	v_mfma_f32_16x16x32_bf16 v[18:21], v[156:159], v[136:139], v[18:21]
	v_mfma_f32_16x16x32_bf16 v[14:17], v[124:127], v[152:155], v[14:17]
	v_mfma_f32_16x16x32_bf16 v[10:13], v[132:135], v[152:155], v[10:13]
	v_mfma_f32_16x16x32_bf16 v[6:9], v[140:143], v[152:155], v[6:9]
	v_mfma_f32_16x16x32_bf16 v[2:5], v[156:159], v[152:155], v[2:5]
	ds_read_b128 v[120:123], v151 offset:1024
	ds_read_b128 v[124:127], v160 offset:17408
	ds_read_b128 v[128:131], v151 offset:3072
	ds_read_b128 v[132:135], v160 offset:19456
	ds_read_b128 v[136:139], v151 offset:5120
	ds_read_b128 v[140:143], v160 offset:21504
	ds_read_b128 v[152:155], v151 offset:7168
	ds_read_b128 v[156:159], v160 offset:23552
	s_waitcnt lgkmcnt(0)
	v_mfma_f32_16x16x32_bf16 v[62:65], v[124:127], v[120:123], v[62:65]
	v_mfma_f32_16x16x32_bf16 v[58:61], v[132:135], v[120:123], v[58:61]
	v_mfma_f32_16x16x32_bf16 v[54:57], v[140:143], v[120:123], v[54:57]
	v_mfma_f32_16x16x32_bf16 v[50:53], v[156:159], v[120:123], v[50:53]
	v_mfma_f32_16x16x32_bf16 v[46:49], v[124:127], v[128:131], v[46:49]
	v_mfma_f32_16x16x32_bf16 v[42:45], v[132:135], v[128:131], v[42:45]
	v_mfma_f32_16x16x32_bf16 v[38:41], v[140:143], v[128:131], v[38:41]
	v_mfma_f32_16x16x32_bf16 v[34:37], v[156:159], v[128:131], v[34:37]
	v_mfma_f32_16x16x32_bf16 v[30:33], v[124:127], v[136:139], v[30:33]
	v_mfma_f32_16x16x32_bf16 v[26:29], v[132:135], v[136:139], v[26:29]
	v_mfma_f32_16x16x32_bf16 v[22:25], v[140:143], v[136:139], v[22:25]
	v_mfma_f32_16x16x32_bf16 v[18:21], v[156:159], v[136:139], v[18:21]
	v_mfma_f32_16x16x32_bf16 v[14:17], v[124:127], v[152:155], v[14:17]
	v_mfma_f32_16x16x32_bf16 v[10:13], v[132:135], v[152:155], v[10:13]
	v_mfma_f32_16x16x32_bf16 v[6:9], v[140:143], v[152:155], v[6:9]
	v_mfma_f32_16x16x32_bf16 v[2:5], v[156:159], v[152:155], v[2:5]
	s_cbranch_scc0 .LBB0_300
	s_waitcnt vmcnt(0)
	s_waitcnt lgkmcnt(0)
	s_barrier
	v_add_u32_e32 v132, v116, v118
	ds_read_b128 v[112:115], v132 offset:53248
	ds_read_b128 v[128:131], v132 offset:54272
	v_add_u32_e32 v133, v116, v117
	ds_read_b128 v[104:107], v133 offset:32768
	ds_read_b128 v[100:103], v132 offset:49152
	ds_read_b128 v[108:111], v132 offset:51200
	s_cmp_gt_i32 s12, 63
	s_cselect_b64 s[48:49], -1, 0
	s_waitcnt lgkmcnt(0)
	v_mfma_f32_16x16x32_bf16 v[120:123], v[112:115], v[104:107], v[54:57]
	s_cmp_lt_i32 s56, 5
	s_cselect_b64 s[12:13], -1, 0
	s_nop 0
	ds_read_b128 v[54:57], v132 offset:55296
	v_mfma_f32_16x16x32_bf16 v[62:65], v[100:103], v[104:107], v[62:65]
	s_and_b64 s[50:51], s[48:49], s[12:13]
	s_and_b64 vcc, exec, s[50:51]
	v_mfma_f32_16x16x32_bf16 v[58:61], v[108:111], v[104:107], v[58:61]
	s_waitcnt lgkmcnt(0)
	v_mfma_f32_16x16x32_bf16 v[104:107], v[54:57], v[104:107], v[50:53]
	s_nop 2
	ds_read_b128 v[50:53], v133 offset:34816
	s_waitcnt lgkmcnt(0)
	v_mfma_f32_16x16x32_bf16 v[46:49], v[100:103], v[50:53], v[46:49]
	v_mfma_f32_16x16x32_bf16 v[42:45], v[108:111], v[50:53], v[42:45]
	v_mfma_f32_16x16x32_bf16 v[38:41], v[112:115], v[50:53], v[38:41]
	v_mfma_f32_16x16x32_bf16 v[34:37], v[54:57], v[50:53], v[34:37]
	ds_read_b128 v[50:53], v133 offset:36864
	s_waitcnt lgkmcnt(0)
	v_mfma_f32_16x16x32_bf16 v[30:33], v[100:103], v[50:53], v[30:33]
	v_mfma_f32_16x16x32_bf16 v[26:29], v[108:111], v[50:53], v[26:29]
	v_mfma_f32_16x16x32_bf16 v[22:25], v[112:115], v[50:53], v[22:25]
	v_mfma_f32_16x16x32_bf16 v[18:21], v[54:57], v[50:53], v[18:21]
	ds_read_b128 v[50:53], v133 offset:38912
	s_waitcnt lgkmcnt(0)
	v_mfma_f32_16x16x32_bf16 v[14:17], v[100:103], v[50:53], v[14:17]
	v_mfma_f32_16x16x32_bf16 v[100:103], v[108:111], v[50:53], v[10:13]
	ds_read_b128 v[108:111], v132 offset:52224
	v_mfma_f32_16x16x32_bf16 v[112:115], v[112:115], v[50:53], v[6:9]
	s_nop 2
	ds_read_b128 v[6:9], v132 offset:50176
	v_mfma_f32_16x16x32_bf16 v[124:127], v[54:57], v[50:53], v[2:5]
	s_nop 2
	ds_read_b128 v[2:5], v133 offset:33792
	s_waitcnt lgkmcnt(0)
	v_mfma_f32_16x16x32_bf16 v[54:57], v[108:111], v[2:5], v[58:61]
	v_mfma_f32_16x16x32_bf16 v[58:61], v[128:131], v[2:5], v[120:123]
	s_nop 2
	ds_read_b128 v[120:123], v132 offset:56320
	v_mfma_f32_16x16x32_bf16 v[50:53], v[6:9], v[2:5], v[62:65]
	s_waitcnt lgkmcnt(0)
	v_mfma_f32_16x16x32_bf16 v[62:65], v[120:123], v[2:5], v[104:107]
	ds_read_b128 v[2:5], v133 offset:35840
	s_nop 1
	ds_read_b128 v[104:107], v133 offset:39936
	s_waitcnt lgkmcnt(0)
	v_mfma_f32_16x16x32_bf16 v[46:49], v[6:9], v[2:5], v[46:49]
	v_mfma_f32_16x16x32_bf16 v[42:45], v[108:111], v[2:5], v[42:45]
	v_mfma_f32_16x16x32_bf16 v[38:41], v[128:131], v[2:5], v[38:41]
	v_mfma_f32_16x16x32_bf16 v[34:37], v[120:123], v[2:5], v[34:37]
	ds_read_b128 v[2:5], v133 offset:37888
	s_waitcnt lgkmcnt(0)
	v_mfma_f32_16x16x32_bf16 v[30:33], v[6:9], v[2:5], v[30:33]
	v_mfma_f32_16x16x32_bf16 v[26:29], v[108:111], v[2:5], v[26:29]
	v_mfma_f32_16x16x32_bf16 v[10:13], v[6:9], v[104:107], v[14:17]
	v_mfma_f32_16x16x32_bf16 v[6:9], v[108:111], v[104:107], v[100:103]
	v_add_u32_e32 v111, s40, v119
	s_nop 0
	v_and_b32_e32 v14, 0xfc0, v111
	v_mov_b32_e32 v15, v0
	v_mfma_f32_16x16x32_bf16 v[22:25], v[128:131], v[2:5], v[22:25]
	v_lshl_add_u64 v[100:101], v[68:69], 0, v[14:15]
	v_lshl_add_u64 v[102:103], v[70:71], 0, v[14:15]
	v_mfma_f32_16x16x32_bf16 v[18:21], v[120:123], v[2:5], v[18:21]
	v_mfma_f32_16x16x32_bf16 v[2:5], v[128:131], v[104:107], v[112:115]
	v_mfma_f32_16x16x32_bf16 v[14:17], v[120:123], v[104:107], v[124:127]
	s_cbranch_vccz .LBB0_303
	global_load_dwordx4 v[104:107], v[100:101], off
	global_load_dwordx4 v[112:115], v[102:103], off
	global_load_dwordx4 v[120:123], v[72:73], off
	global_load_dwordx4 v[124:127], v[74:75], off
	s_waitcnt vmcnt(0)
	v_mul_f32_e32 v130, v52, v106
	v_pk_mul_f32 v[108:109], v[50:51], v[112:113]
	v_pk_mul_f32 v[112:113], v[54:55], v[112:113]
	v_mul_f32_e32 v132, v56, v114
	v_mul_f32_e32 v106, v56, v106
	v_mul_f32_e32 v134, v52, v114
	v_mul_f32_e32 v136, v60, v122
	v_mul_f32_e32 v138, v64, v126
	v_mul_f32_e32 v122, v64, v122
	v_mul_f32_e32 v140, v60, v126
	v_mov_b32_e32 v56, v53
	v_mov_b32_e32 v114, v107
	v_mov_b32_e32 v52, v57
	v_mov_b32_e32 v64, v61
	v_mov_b32_e32 v126, v123
	v_mov_b32_e32 v60, v65
	v_pk_mul_f32 v[142:143], v[56:57], v[114:115]
	v_pk_mul_f32 v[52:53], v[52:53], v[114:115]
	v_pk_fma_f32 v[50:51], v[50:51], v[104:105], v[112:113] neg_lo:[0,0,1] neg_hi:[0,0,1]
	v_pk_fma_f32 v[54:55], v[54:55], v[104:105], v[108:109]
	v_pk_mul_f32 v[104:105], v[64:65], v[126:127]
	v_pk_mul_f32 v[60:61], v[60:61], v[126:127]
	v_pk_mul_f32 v[128:129], v[58:59], v[124:125]
	v_pk_mul_f32 v[124:125], v[62:63], v[124:125]
	v_mov_b32_e32 v131, v142
	v_mov_b32_e32 v133, v143
	v_mov_b32_e32 v107, v52
	v_mov_b32_e32 v135, v53
	v_mov_b32_e32 v137, v104
	v_mov_b32_e32 v139, v105
	v_mov_b32_e32 v123, v60
	v_mov_b32_e32 v141, v61
	v_pk_add_f32 v[52:53], v[130:131], v[132:133] neg_lo:[0,1] neg_hi:[0,1]
	v_pk_add_f32 v[56:57], v[106:107], v[134:135]
	v_pk_fma_f32 v[58:59], v[58:59], v[120:121], v[124:125] neg_lo:[0,0,1] neg_hi:[0,0,1]
	v_pk_add_f32 v[60:61], v[136:137], v[138:139] neg_lo:[0,1] neg_hi:[0,1]
	v_pk_fma_f32 v[62:63], v[62:63], v[120:121], v[128:129]
	v_pk_add_f32 v[64:65], v[122:123], v[140:141]
